# attention QK: 8 K-fragment ds_reads hoisted above DMA issue, counted lgkmcnt waits
# baseline (speedup 1.0000x reference)
.LBB0_734:
	v_add_u32_e32 v128, s78, v145
	ds_read_b128 v[124:127], v128 offset:1024
	ds_read_b128 v[120:123], v128
	ds_read_b32 v166, v156 offset:8192
	s_add_i32 s54, s19, -2
	s_cmp_lt_i32 s54, s18
	s_cselect_b64 s[52:53], -1, 0
	s_cmp_ge_i32 s54, s18
	v_lshl_add_u64 v[134:135], s[50:51], 0, v[132:133]
	s_cbranch_scc1 .LBB0_738
	v_add_u32_e32 v72, s79, v147
	v_add_u32_e32 v73, s79, v149
	v_add_u32_e32 v74, s79, v151
	v_add_u32_e32 v75, s79, v153
	ds_read_b128 v[64:67], v72
	ds_read_b128 v[168:171], v73
	ds_read_b128 v[172:175], v74
	ds_read_b128 v[176:179], v75
	ds_read_b128 v[180:183], v72 offset:128
	ds_read_b128 v[184:187], v73 offset:128
	ds_read_b128 v[188:191], v74 offset:128
	ds_read_b128 v[192:195], v75 offset:128
	s_mov_b64 s[54:55], 0xe404000
	v_lshl_add_u64 v[76:77], v[134:135], 0, s[54:55]
	s_add_i32 m0, s96, 0x8000
	s_mov_b64 s[54:55], 0xe406000
	global_load_lds_dwordx4 v[76:77], off
	v_lshl_add_u64 v[76:77], v[134:135], 0, s[54:55]
	s_add_i32 m0, s96, 0xa000
	s_mov_b64 s[54:55], 0xe804000
	global_load_lds_dwordx4 v[76:77], off
	v_lshl_add_u64 v[76:77], v[134:135], 0, s[54:55]
	s_add_i32 m0, s96, 0xc000
	s_mov_b64 s[54:55], 0xe806000
	global_load_lds_dwordx4 v[76:77], off
	v_lshl_add_u64 v[76:77], v[134:135], 0, s[54:55]
	s_add_i32 m0, s96, 0xe000
	s_cmp_gt_i32 s19, s18
	global_load_lds_dwordx4 v[76:77], off
	s_cbranch_scc1 .LBB0_737
	v_lshl_add_u64 v[76:77], s[50:51], 0, v[130:131]
	s_mov_b64 s[54:55], 0xc40a000
	v_lshl_add_u64 v[78:79], v[76:77], 0, s[54:55]
	s_mov_b64 s[54:55], 0xc408000
	s_mov_b32 m0, s97
	v_lshl_add_u64 v[76:77], v[76:77], 0, s[54:55]
	global_load_lds_dwordx4 v[76:77], off
	s_mov_b32 m0, s26
	s_nop 0
	global_load_lds_dwordx4 v[78:79], off
.LBB0_737:
	s_waitcnt lgkmcnt(7)
	v_mfma_f32_32x32x16_bf16 v[64:79], v[64:67], v[80:83], 0
	s_waitcnt lgkmcnt(6)
	v_mfma_f32_32x32x16_bf16 v[64:79], v[168:171], v[84:87], v[64:79]
	s_waitcnt lgkmcnt(5)
	v_mfma_f32_32x32x16_bf16 v[64:79], v[172:175], v[88:91], v[64:79]
	s_waitcnt lgkmcnt(4)
	v_mfma_f32_32x32x16_bf16 v[64:79], v[176:179], v[92:95], v[64:79]
	s_waitcnt lgkmcnt(3)
	v_mfma_f32_32x32x16_bf16 v[64:79], v[180:183], v[96:99], v[64:79]
	s_waitcnt lgkmcnt(2)
	v_mfma_f32_32x32x16_bf16 v[64:79], v[184:187], v[100:103], v[64:79]
	s_waitcnt lgkmcnt(1)
	v_mfma_f32_32x32x16_bf16 v[64:79], v[188:191], v[104:107], v[64:79]
	s_waitcnt lgkmcnt(0)
	v_mfma_f32_32x32x16_bf16 v[64:79], v[192:195], v[108:111], v[64:79]

.LBB0_748:
	ds_read_b128 v[124:127], v128 offset:5120
	ds_read_b128 v[120:123], v128 offset:4096
	ds_read_b32 v128, v156 offset:8448
	s_cmp_gt_i32 s19, s18
	s_cselect_b64 s[52:53], -1, 0
	s_cmp_le_i32 s19, s18
	s_cselect_b64 s[54:55], -1, 0
	s_and_b64 vcc, exec, s[52:53]
	s_cbranch_vccnz .LBB0_752
	ds_read_b128 v[64:67], v148
	ds_read_b128 v[168:171], v150
	ds_read_b128 v[172:175], v152
	ds_read_b128 v[176:179], v154
	ds_read_b128 v[180:183], v148 offset:128
	ds_read_b128 v[184:187], v150 offset:128
	ds_read_b128 v[188:191], v152 offset:128
	ds_read_b128 v[192:195], v154 offset:128
	s_mov_b64 s[56:57], 0xe408000
	s_mov_b32 m0, s96
	v_lshl_add_u64 v[76:77], v[134:135], 0, s[56:57]
	s_mov_b64 s[56:57], 0xe40a000
	global_load_lds_dwordx4 v[76:77], off
	v_lshl_add_u64 v[76:77], v[134:135], 0, s[56:57]
	s_mov_b32 m0, s6
	s_mov_b64 s[56:57], 0xe808000
	global_load_lds_dwordx4 v[76:77], off
	v_lshl_add_u64 v[76:77], v[134:135], 0, s[56:57]
	s_mov_b32 m0, s7
	s_mov_b64 s[56:57], 0xe80a000
	global_load_lds_dwordx4 v[76:77], off
	v_lshl_add_u64 v[76:77], v[134:135], 0, s[56:57]
	s_mov_b32 m0, s24
	s_add_i32 s56, s19, 1
	global_load_lds_dwordx4 v[76:77], off
	s_cmp_gt_i32 s56, s18
	s_cbranch_scc1 .LBB0_751
	v_lshl_add_u64 v[76:77], s[50:51], 0, v[130:131]
	s_mov_b64 s[56:57], 0xc40e000
	v_lshl_add_u64 v[78:79], v[76:77], 0, s[56:57]
	s_mov_b64 s[56:57], 0xc40c000
	s_mov_b32 m0, s27
	v_lshl_add_u64 v[76:77], v[76:77], 0, s[56:57]
	global_load_lds_dwordx4 v[76:77], off
	s_mov_b32 m0, s62
	s_nop 0
	global_load_lds_dwordx4 v[78:79], off
